# P5a mirror rows: all 12 gather loads of a row task in flight together, counted waits (was 4 serial load-wait-store chains)
# speedup vs baseline: 1.0122x; 1.0011x over previous
; __global__ void __launch_bounds__(NTHR, 2) fwd_kernel(Args a) {
;     ...
;       for (int task = gw; task < NB * 1023; task += NGW) { const int b = task / 1023, row = 1 + task % 1023;
;           const bf16_t* src = Ff + (size_t)(b * SEQ + row) * FNW; bf16_t* dst = Ff + (size_t)(b * SEQ + SEQ - row) * FNW;
; #pragma unroll
;           for (int g = 0; g < 4; ++g) { const bf16_t* sg = src + g * 256; const int c = 4 * lane;
;               const unsigned e0 = sg[(256 - c) & 255], e1 = sg[255 - c], e2 = sg[254 - c], e3 = sg[253 - c];
;               u32x2 w; w.x = e0 | (e1 << 16); w.y = e2 | (e3 << 16); *(u32x2*)(dst + g * 256 + c) = w; } }
.LBB0_1337:
	s_mul_hi_i32 s6, s5, 0x80200803
	s_add_i32 s6, s6, s5
	s_lshr_b32 s7, s6, 31
	s_ashr_i32 s6, s6, 9
	s_add_i32 s8, s6, s7
	s_mul_i32 s6, s8, 0x401
	s_add_i32 s6, s5, s6
	s_add_i32 s6, s6, 1
	s_ashr_i32 s7, s6, 31
	s_lshl_b64 s[6:7], s[6:7], 11
	s_add_u32 s6, s78, s6
	s_addc_u32 s7, s79, s7
	v_lshl_add_u64 v[8:9], v[4:5], 1, s[6:7]
	global_load_ushort v16, v1, s[6:7]
	global_load_dword v17, v6, s[6:7]
	global_load_ushort v24, v[8:9], off offset:6
	global_load_ushort v18, v1, s[6:7] offset:512
	global_load_dword v19, v6, s[6:7] offset:512
	global_load_ushort v25, v[8:9], off offset:518
	global_load_ushort v20, v1, s[6:7] offset:1024
	global_load_dword v21, v6, s[6:7] offset:1024
	global_load_ushort v26, v[8:9], off offset:1030
	global_load_ushort v22, v1, s[6:7] offset:1536
	global_load_dword v23, v6, s[6:7] offset:1536
	global_load_ushort v27, v[8:9], off offset:1542
	s_mulk_i32 s8, 0xbff
	s_add_i32 s8, s3, s8
	s_ashr_i32 s9, s8, 31
	s_lshl_b64 s[8:9], s[8:9], 11
	v_lshl_add_u64 v[10:11], v[2:3], 0, s[8:9]
	s_add_i32 s5, s5, s10
	s_sub_i32 s3, s3, s10
	s_cmpk_gt_i32 s5, 0xffb
	s_waitcnt vmcnt(9)
	v_lshl_or_b32 v16, v24, 16, v16
	v_alignbit_b32 v17, v17, v17, 16
	global_store_dwordx2 v[10:11], v[16:17], off
	s_waitcnt vmcnt(7)
	v_lshl_or_b32 v18, v25, 16, v18
	v_alignbit_b32 v19, v19, v19, 16
	global_store_dwordx2 v[10:11], v[18:19], off offset:512
	s_waitcnt vmcnt(5)
	v_lshl_or_b32 v20, v26, 16, v20
	v_alignbit_b32 v21, v21, v21, 16
	global_store_dwordx2 v[10:11], v[20:21], off offset:1024
	s_waitcnt vmcnt(3)
	v_lshl_or_b32 v22, v27, 16, v22
	v_alignbit_b32 v23, v23, v23, 16
	global_store_dwordx2 v[10:11], v[22:23], off offset:1536
	s_cbranch_scc0 .LBB0_1337
